# grid barrier: each block's agent-scope L1 invalidate is issued and completed at arrival, before its XSUB arrival add (so all invalidates complete before the flag); post-flag invalidates dropped
# speedup vs baseline: 1.0189x; 1.0153x over previous
.LBB0_83:
	s_or_b64 exec, exec, s[4:5]
	s_mov_b64 s[6:7], exec
	v_readlane_b32 s3, v237, 2
	s_lshl_b32 s3, s3, 8
	v_mbcnt_lo_u32_b32 v1, s6, 0
	s_add_u32 s4, s92, s3
	v_mbcnt_hi_u32_b32 v1, s7, v1
	s_addc_u32 s5, s93, 0
	v_cmp_eq_u32_e32 vcc, 0, v1
	s_and_saveexec_b64 s[8:9], vcc
	s_cbranch_execz .LBB0_85
	s_bcnt1_i32_b64 s3, s[6:7]
	v_mov_b32_e32 v3, 0x1000
	v_mov_b32_e32 v4, s3
	buffer_inv sc1
	s_waitcnt vmcnt(0)
	global_atomic_add v3, v3, v4, s[4:5] offset:1024 sc0

.LBB0_98:
	s_or_b64 exec, exec, s[8:9]
	s_waitcnt vmcnt(0) lgkmcnt(0)
	s_waitcnt vmcnt(0)

.LBB0_116:
	s_or_b64 exec, exec, s[6:7]
	s_mov_b64 s[6:7], exec
	v_mbcnt_lo_u32_b32 v0, s6, 0
	v_mbcnt_hi_u32_b32 v0, s7, v0
	v_cmp_eq_u32_e32 vcc, 0, v0
	s_waitcnt vmcnt(0)
	s_and_saveexec_b64 s[8:9], vcc
	s_cbranch_execz .LBB0_118
	s_bcnt1_i32_b64 s3, s[6:7]
	v_mov_b32_e32 v0, 0x2000
	v_mov_b32_e32 v1, s3

.LBB0_138:
	s_or_b64 exec, exec, s[6:7]
	s_mov_b64 s[8:9], exec
	v_readlane_b32 s0, v237, 2
	s_lshl_b32 s0, s0, 8
	v_mbcnt_lo_u32_b32 v1, s8, 0
	s_add_u32 s6, s92, s0
	v_mbcnt_hi_u32_b32 v1, s9, v1
	s_addc_u32 s7, s93, 0
	v_cmp_eq_u32_e32 vcc, 0, v1
	s_and_saveexec_b64 s[12:13], vcc
	s_cbranch_execz .LBB0_140
	s_bcnt1_i32_b64 s0, s[8:9]
	v_mov_b32_e32 v3, 0x1000
	v_mov_b32_e32 v4, s0
	buffer_inv sc1
	s_waitcnt vmcnt(0)
	global_atomic_add v3, v3, v4, s[6:7] offset:1024 sc0

.LBB0_153:
	s_or_b64 exec, exec, s[12:13]
	s_waitcnt vmcnt(0) lgkmcnt(0)
	s_waitcnt vmcnt(0)

.LBB0_171:
	s_or_b64 exec, exec, s[8:9]
	s_mov_b64 s[8:9], exec
	v_mbcnt_lo_u32_b32 v0, s8, 0
	v_mbcnt_hi_u32_b32 v0, s9, v0
	v_cmp_eq_u32_e32 vcc, 0, v0
	s_waitcnt vmcnt(0)
	s_and_saveexec_b64 s[12:13], vcc
	s_cbranch_execz .LBB0_173
	s_bcnt1_i32_b64 s0, s[8:9]
	v_mov_b32_e32 v0, 0x2000
	v_mov_b32_e32 v1, s0

.LBB0_411:
	s_or_b64 exec, exec, s[6:7]
	s_mov_b64 s[8:9], exec
	v_readlane_b32 s0, v237, 2
	s_lshl_b32 s0, s0, 8
	v_mbcnt_lo_u32_b32 v1, s8, 0
	s_add_u32 s6, s92, s0
	v_mbcnt_hi_u32_b32 v1, s9, v1
	s_addc_u32 s7, s93, 0
	v_cmp_eq_u32_e32 vcc, 0, v1
	s_and_saveexec_b64 s[10:11], vcc
	s_cbranch_execz .LBB0_413
	s_bcnt1_i32_b64 s0, s[8:9]
	v_mov_b32_e32 v3, 0x1000
	v_mov_b32_e32 v4, s0
	buffer_inv sc1
	s_waitcnt vmcnt(0)
	global_atomic_add v3, v3, v4, s[6:7] offset:1024 sc0

.LBB0_426:
	s_or_b64 exec, exec, s[10:11]
	s_waitcnt vmcnt(0) lgkmcnt(0)
	s_waitcnt vmcnt(0)

.LBB0_444:
	s_or_b64 exec, exec, s[8:9]
	s_mov_b64 s[8:9], exec
	v_mbcnt_lo_u32_b32 v0, s8, 0
	v_mbcnt_hi_u32_b32 v0, s9, v0
	v_cmp_eq_u32_e32 vcc, 0, v0
	s_waitcnt vmcnt(0)
	s_and_saveexec_b64 s[10:11], vcc
	s_cbranch_execz .LBB0_446
	s_bcnt1_i32_b64 s0, s[8:9]
	v_mov_b32_e32 v0, 0x2000
	v_mov_b32_e32 v1, s0

.LBB0_599:
	s_or_b64 exec, exec, s[12:13]
	s_mov_b64 s[20:21], exec
	v_readlane_b32 s0, v237, 2
	s_lshl_b32 s0, s0, 8
	v_mbcnt_lo_u32_b32 v1, s20, 0
	s_add_u32 s12, s92, s0
	v_mbcnt_hi_u32_b32 v1, s21, v1
	s_addc_u32 s13, s93, 0
	v_cmp_eq_u32_e32 vcc, 0, v1
	s_and_saveexec_b64 s[22:23], vcc
	s_cbranch_execz .LBB0_601
	s_bcnt1_i32_b64 s0, s[20:21]
	v_mov_b32_e32 v3, 0x1000
	v_mov_b32_e32 v4, s0
	buffer_inv sc1
	s_waitcnt vmcnt(0)
	global_atomic_add v3, v3, v4, s[12:13] offset:1024 sc0

.LBB0_614:
	s_or_b64 exec, exec, s[22:23]
	s_waitcnt vmcnt(0) lgkmcnt(0)
	s_waitcnt vmcnt(0)

.LBB0_632:
	s_or_b64 exec, exec, s[20:21]
	s_mov_b64 s[20:21], exec
	v_mbcnt_lo_u32_b32 v0, s20, 0
	v_mbcnt_hi_u32_b32 v0, s21, v0
	v_cmp_eq_u32_e32 vcc, 0, v0
	s_waitcnt vmcnt(0)
	s_and_saveexec_b64 s[22:23], vcc
	s_cbranch_execz .LBB0_634
	s_bcnt1_i32_b64 s0, s[20:21]
	v_mov_b32_e32 v0, 0x2000
	v_mov_b32_e32 v1, s0

.LBB0_686:
	s_or_b64 exec, exec, s[12:13]
	s_mov_b64 s[16:17], exec
	v_readlane_b32 s0, v237, 2
	s_lshl_b32 s0, s0, 8
	v_mbcnt_lo_u32_b32 v1, s16, 0
	s_add_u32 s12, s92, s0
	v_mbcnt_hi_u32_b32 v1, s17, v1
	s_addc_u32 s13, s93, 0
	v_cmp_eq_u32_e32 vcc, 0, v1
	s_and_saveexec_b64 s[20:21], vcc
	s_cbranch_execz .LBB0_688
	s_bcnt1_i32_b64 s0, s[16:17]
	v_mov_b32_e32 v3, 0x1000
	v_mov_b32_e32 v4, s0
	buffer_inv sc1
	s_waitcnt vmcnt(0)
	global_atomic_add v3, v3, v4, s[12:13] offset:1024 sc0

.LBB0_701:
	s_or_b64 exec, exec, s[20:21]
	s_waitcnt vmcnt(0) lgkmcnt(0)
	s_waitcnt vmcnt(0)

.LBB0_719:
	s_or_b64 exec, exec, s[16:17]
	s_mov_b64 s[16:17], exec
	v_mbcnt_lo_u32_b32 v0, s16, 0
	v_mbcnt_hi_u32_b32 v0, s17, v0
	v_cmp_eq_u32_e32 vcc, 0, v0
	s_waitcnt vmcnt(0)
	s_and_saveexec_b64 s[20:21], vcc
	s_cbranch_execz .LBB0_721
	s_bcnt1_i32_b64 s0, s[16:17]
	v_mov_b32_e32 v0, 0x2000
	v_mov_b32_e32 v1, s0

.LBB0_786:
	s_or_b64 exec, exec, s[16:17]
	s_mov_b64 s[20:21], exec
	v_readlane_b32 s0, v237, 2
	s_lshl_b32 s0, s0, 8
	v_mbcnt_lo_u32_b32 v1, s20, 0
	s_add_u32 s16, s92, s0
	v_mbcnt_hi_u32_b32 v1, s21, v1
	s_addc_u32 s17, s93, 0
	v_cmp_eq_u32_e32 vcc, 0, v1
	s_and_saveexec_b64 s[22:23], vcc
	s_cbranch_execz .LBB0_788
	s_bcnt1_i32_b64 s0, s[20:21]
	v_mov_b32_e32 v3, 0x1000
	v_mov_b32_e32 v4, s0
	buffer_inv sc1
	s_waitcnt vmcnt(0)
	global_atomic_add v3, v3, v4, s[16:17] offset:1024 sc0
